# P0 xn section: row loads software-pipelined one iteration ahead of the stores (second register set)
# baseline (speedup 1.0000x reference)
; __global__ void __launch_bounds__(NWAVES * 64, 2) mk_fwd(Params P) {
;     ...
;         { f32x4 wn[4];
; #pragma unroll
;           for (int j = 0; j < 4; ++j) wn[j] = *((const f32x4*)P.attn_norm + lane + 64 * j);
;           for (int m0 = gw * 4; m0 < M; m0 += NGW * 4) {
;             f32x4 v[4][4];
; #pragma unroll
;             for (int q = 0; q < 4; ++q) { const f32x4* xr = (const f32x4*)xrow(P.xp, P.xs, m0 + q) + lane;
; #pragma unroll
;                 for (int j = 0; j < 4; ++j) v[q][j] = xr[64 * j]; }
.LBB0_208:
	s_or_b64 exec, exec, s[8:9]
	s_cmpk_lt_i32 s12, 0x3000
	v_mov_b32_e32 v19, 0
	s_mov_b64 s[90:91], s[72:73]
	s_cbranch_scc0 .LBB0_211
	v_lshlrev_b32_e32 v1, 4, v193
	global_load_dwordx4 v[2:5], v1, s[20:21] offset:3072
	global_load_dwordx4 v[6:9], v1, s[20:21] offset:2048
	global_load_dwordx4 v[10:13], v1, s[20:21] offset:1024
	global_load_dwordx4 v[14:17], v1, s[20:21]
	s_lshl_b32 s20, s12, 2
	s_lshl_b32 s22, s90, 5
	s_ashr_i32 s21, s20, 31
	s_ashr_i32 s23, s22, 31
	s_lshl_b64 s[0:1], s[20:21], 11
	s_add_u32 s0, s58, s0
	v_lshlrev_b32_e32 v18, 3, v193
	s_addc_u32 s1, s59, s1
	v_lshl_add_u64 v[18:19], s[0:1], 0, v[18:19]
	s_mov_b64 s[0:1], 0x5000000
	v_lshl_add_u64 v[82:83], v[18:19], 0, s[0:1]
	s_waitcnt lgkmcnt(0)
	s_lshl_b64 s[42:43], s[22:23], 11
	v_mov_b32_e32 v86, 0x358637bd
	s_mov_b32 s3, 0xf800000
	v_mov_b32_e32 v87, 0x260
	s_movk_i32 s12, 0x7fff
	s_mov_b32 s13, 0xffff0000
	s_movk_i32 s33, 0x1000
	s_add_i32 s0, s20, 0xffffc000
	s_cmpk_lt_i32 s20, 0x4000
	s_cselect_b32 s1, s21, 0
	s_cselect_b32 s0, s20, s0
	s_cselect_b32 s4, s17, s19
	s_cselect_b32 s5, s16, s18
	s_lshl_b64 s[0:1], s[0:1], 12
	s_add_u32 s0, s5, s0
	s_addc_u32 s1, s4, s1
	global_load_dwordx4 v[182:185], v1, s[0:1]
	global_load_dwordx4 v[176:179], v1, s[0:1] offset:1024
	global_load_dwordx4 v[172:175], v1, s[0:1] offset:2048
	global_load_dwordx4 v[168:171], v1, s[0:1] offset:3072
	s_add_u32 s0, s20, 1
	s_addc_u32 s1, s21, 0
	s_add_i32 s4, s20, 0xffffc001
	s_cmpk_lt_i32 s0, 0x4000
	s_cselect_b32 s1, s1, 0
	s_cselect_b32 s0, s0, s4
	s_cselect_b32 s4, s17, s19
	s_cselect_b32 s5, s16, s18
	s_lshl_b64 s[0:1], s[0:1], 12
	s_add_u32 s0, s5, s0
	s_addc_u32 s1, s4, s1
	global_load_dwordx4 v[164:167], v1, s[0:1]
	global_load_dwordx4 v[160:163], v1, s[0:1] offset:1024
	global_load_dwordx4 v[156:159], v1, s[0:1] offset:2048
	global_load_dwordx4 v[152:155], v1, s[0:1] offset:3072
	s_add_u32 s0, s20, 2
	s_addc_u32 s1, s21, 0
	s_add_i32 s4, s20, 0xffffc002
	s_cmpk_lt_i32 s0, 0x4000
	s_cselect_b32 s1, s1, 0
	s_cselect_b32 s0, s0, s4
	s_cselect_b32 s4, s17, s19
	s_cselect_b32 s5, s16, s18
	s_lshl_b64 s[0:1], s[0:1], 12
	s_add_u32 s0, s5, s0
	s_addc_u32 s1, s4, s1
	global_load_dwordx4 v[148:151], v1, s[0:1]
	global_load_dwordx4 v[144:147], v1, s[0:1] offset:1024
	global_load_dwordx4 v[140:143], v1, s[0:1] offset:2048
	global_load_dwordx4 v[136:139], v1, s[0:1] offset:3072
	s_add_u32 s0, s20, 3
	s_addc_u32 s1, s21, 0
	s_add_i32 s4, s20, 0xffffc003
	s_cmpk_lt_i32 s0, 0x4000
	s_cselect_b32 s1, s1, 0
	s_cselect_b32 s0, s0, s4
	s_cselect_b32 s4, s17, s19
	s_cselect_b32 s5, s16, s18
	s_lshl_b64 s[0:1], s[0:1], 12
	s_add_u32 s0, s5, s0
	s_addc_u32 s1, s4, s1
	global_load_dwordx4 v[132:135], v1, s[0:1]
	global_load_dwordx4 v[128:131], v1, s[0:1] offset:1024
	global_load_dwordx4 v[124:127], v1, s[0:1] offset:2048
	global_load_dwordx4 v[120:123], v1, s[0:1] offset:3072
	s_mov_b32 s99, 0
.LBB0_210:
	s_cmp_eq_u32 s99, 0
	s_cbranch_scc1 .Lxn_first
	s_waitcnt vmcnt(16)
	s_branch .Lxn_go
.Lxn_first:
	s_waitcnt vmcnt(0)
	s_mov_b32 s99, 1
.Lxn_go:
	v_mov_b64_e32 v[18:19], v[120:121]
	v_mov_b64_e32 v[20:21], v[122:123]
	v_mov_b64_e32 v[22:23], v[124:125]
	v_mov_b64_e32 v[24:25], v[126:127]
	v_mov_b64_e32 v[26:27], v[128:129]
	v_mov_b64_e32 v[28:29], v[130:131]
	v_mov_b64_e32 v[30:31], v[132:133]
	v_mov_b64_e32 v[32:33], v[134:135]
	v_mov_b64_e32 v[34:35], v[136:137]
	v_mov_b64_e32 v[36:37], v[138:139]
	v_mov_b64_e32 v[38:39], v[140:141]
	v_mov_b64_e32 v[40:41], v[142:143]
	v_mov_b64_e32 v[42:43], v[144:145]
	v_mov_b64_e32 v[44:45], v[146:147]
	v_mov_b64_e32 v[46:47], v[148:149]
	v_mov_b64_e32 v[48:49], v[150:151]
	v_mov_b64_e32 v[50:51], v[152:153]
	v_mov_b64_e32 v[52:53], v[154:155]
	v_mov_b64_e32 v[54:55], v[156:157]
	v_mov_b64_e32 v[56:57], v[158:159]
	v_mov_b64_e32 v[58:59], v[160:161]
	v_mov_b64_e32 v[60:61], v[162:163]
	v_mov_b64_e32 v[62:63], v[164:165]
	v_mov_b64_e32 v[64:65], v[166:167]
	v_mov_b64_e32 v[66:67], v[168:169]
	v_mov_b64_e32 v[68:69], v[170:171]
	v_mov_b64_e32 v[70:71], v[172:173]
	v_mov_b64_e32 v[72:73], v[174:175]
	v_mov_b64_e32 v[74:75], v[176:177]
	v_mov_b64_e32 v[76:77], v[178:179]
	v_mov_b64_e32 v[78:79], v[182:183]
	v_mov_b64_e32 v[80:81], v[184:185]
	s_add_u32 s20, s20, s22
	s_addc_u32 s21, s21, s23
	s_cmp_gt_i32 s20, 0xbfff
	s_cselect_b32 s98, 1, 0
	s_cbranch_scc1 .Lxn_noload
	s_add_i32 s0, s20, 0xffffc000
	s_cmpk_lt_i32 s20, 0x4000
	s_cselect_b32 s1, s21, 0
	s_cselect_b32 s0, s20, s0
	s_cselect_b32 s4, s17, s19
	s_cselect_b32 s5, s16, s18
	s_lshl_b64 s[0:1], s[0:1], 12
	s_add_u32 s0, s5, s0
	s_addc_u32 s1, s4, s1
	global_load_dwordx4 v[182:185], v1, s[0:1]
	global_load_dwordx4 v[176:179], v1, s[0:1] offset:1024
	global_load_dwordx4 v[172:175], v1, s[0:1] offset:2048
	global_load_dwordx4 v[168:171], v1, s[0:1] offset:3072
	s_add_u32 s0, s20, 1
	s_addc_u32 s1, s21, 0
	s_add_i32 s4, s20, 0xffffc001
	s_cmpk_lt_i32 s0, 0x4000
	s_cselect_b32 s1, s1, 0
	s_cselect_b32 s0, s0, s4
	s_cselect_b32 s4, s17, s19
	s_cselect_b32 s5, s16, s18
	s_lshl_b64 s[0:1], s[0:1], 12
	s_add_u32 s0, s5, s0
	s_addc_u32 s1, s4, s1
	global_load_dwordx4 v[164:167], v1, s[0:1]
	global_load_dwordx4 v[160:163], v1, s[0:1] offset:1024
	global_load_dwordx4 v[156:159], v1, s[0:1] offset:2048
	global_load_dwordx4 v[152:155], v1, s[0:1] offset:3072
	s_add_u32 s0, s20, 2
	s_addc_u32 s1, s21, 0
	s_add_i32 s4, s20, 0xffffc002
	s_cmpk_lt_i32 s0, 0x4000
	s_cselect_b32 s1, s1, 0
	s_cselect_b32 s0, s0, s4
	s_cselect_b32 s4, s17, s19
	s_cselect_b32 s5, s16, s18
	s_lshl_b64 s[0:1], s[0:1], 12
	s_add_u32 s0, s5, s0
	s_addc_u32 s1, s4, s1
	global_load_dwordx4 v[148:151], v1, s[0:1]
	global_load_dwordx4 v[144:147], v1, s[0:1] offset:1024
	global_load_dwordx4 v[140:143], v1, s[0:1] offset:2048
	global_load_dwordx4 v[136:139], v1, s[0:1] offset:3072
	s_add_u32 s0, s20, 3
	s_addc_u32 s1, s21, 0
	s_add_i32 s4, s20, 0xffffc003
	s_cmpk_lt_i32 s0, 0x4000
	s_cselect_b32 s1, s1, 0
	s_cselect_b32 s0, s0, s4
	s_cselect_b32 s4, s17, s19
	s_cselect_b32 s5, s16, s18
	s_lshl_b64 s[0:1], s[0:1], 12
	s_add_u32 s0, s5, s0
	s_addc_u32 s1, s4, s1
	global_load_dwordx4 v[132:135], v1, s[0:1]
	global_load_dwordx4 v[128:131], v1, s[0:1] offset:1024
	global_load_dwordx4 v[124:127], v1, s[0:1] offset:2048
	global_load_dwordx4 v[120:123], v1, s[0:1] offset:3072
; __device__ __forceinline__ float wave_sum(float v) { v = row16_sum(v); v = swap_add16(v, v); return swap_add32(v, v); }
; __global__ void __launch_bounds__(NWAVES * 64, 2) mk_fwd(Params P) {
;     ...
;             for (int q = 0; q < 4; ++q) { float s = 0.f;
; #pragma unroll
;                 for (int j = 0; j < 4; ++j) s += (v[q][j][0] * v[q][j][0] + v[q][j][1] * v[q][j][1]) + (v[q][j][2] * v[q][j][2] + v[q][j][3] * v[q][j][3]);
;                 const float rstd = 1.0f / sqrtf(wave_sum(s) * (1.0f / D) + EPS);
.Lxn_noload:
	v_add_co_u32_e32 v84, vcc, s33, v82
	s_nop 1
	v_addc_co_u32_e32 v85, vcc, 0, v83, vcc
	v_mul_f32_e32 v88, v79, v79
	v_mul_f32_e32 v89, v81, v81
	v_mul_f32_e32 v90, v75, v75
	v_mul_f32_e32 v91, v77, v77
	v_mul_f32_e32 v92, v71, v71
	v_mul_f32_e32 v93, v73, v73
	v_fmac_f32_e32 v88, v78, v78
	v_fmac_f32_e32 v89, v80, v80
	v_fmac_f32_e32 v90, v74, v74
	v_fmac_f32_e32 v91, v76, v76
	v_mul_f32_e32 v94, v67, v67
	v_mul_f32_e32 v95, v69, v69
	v_fmac_f32_e32 v92, v70, v70
	v_fmac_f32_e32 v93, v72, v72
	v_add_f32_e32 v88, v88, v89
	v_add_f32_e32 v89, v90, v91
	v_fmac_f32_e32 v94, v66, v66
	v_fmac_f32_e32 v95, v68, v68
	v_add_f32_e32 v90, v92, v93
	v_add_f32_e32 v88, v88, v89
	v_add_f32_e32 v91, v94, v95
	v_add_f32_e32 v88, v88, v90
	v_add_f32_e32 v88, v88, v91
	v_mul_f32_e32 v89, v63, v63
	v_mul_f32_e32 v90, v65, v65
	v_add_f32_dpp v88, v88, v88 quad_perm:[1,0,3,2] row_mask:0xf bank_mask:0xf bound_ctrl:1
	v_mul_f32_e32 v91, v59, v59
	v_mul_f32_e32 v92, v61, v61
	v_add_f32_dpp v88, v88, v88 quad_perm:[2,3,0,1] row_mask:0xf bank_mask:0xf bound_ctrl:1
	v_mul_f32_e32 v93, v55, v55
	v_mul_f32_e32 v94, v57, v57
	v_add_f32_dpp v88, v88, v88 row_half_mirror row_mask:0xf bank_mask:0xf bound_ctrl:1
	v_fmac_f32_e32 v89, v62, v62
	v_fmac_f32_e32 v90, v64, v64
	v_fmac_f32_e32 v91, v58, v58
	v_fmac_f32_e32 v92, v60, v60
	v_mul_f32_e32 v95, v51, v51
	v_mul_f32_e32 v96, v53, v53
	v_fmac_f32_e32 v93, v54, v54
	v_fmac_f32_e32 v94, v56, v56
	v_add_f32_dpp v88, v88, v88 row_mirror row_mask:0xf bank_mask:0xf bound_ctrl:1
	v_add_f32_e32 v89, v89, v90
	v_add_f32_e32 v90, v91, v92
	v_fmac_f32_e32 v95, v50, v50
	v_fmac_f32_e32 v96, v52, v52
	v_add_f32_e32 v91, v93, v94
	v_mov_b32_e32 v93, v88
	v_add_f32_e32 v89, v89, v90
	v_add_f32_e32 v92, v95, v96
	v_permlane16_swap_b32_e32 v88, v93
	v_add_f32_e32 v89, v89, v91
	v_add_f32_e32 v88, v88, v93
	v_add_f32_e32 v89, v89, v92
	v_mov_b32_e32 v90, v88
	s_nop 1
	v_permlane32_swap_b32_e32 v88, v90
	v_add_f32_dpp v89, v89, v89 quad_perm:[1,0,3,2] row_mask:0xf bank_mask:0xf bound_ctrl:1
	v_mul_f32_e32 v91, v47, v47
	v_mul_f32_e32 v92, v49, v49
	v_add_f32_dpp v89, v89, v89 quad_perm:[2,3,0,1] row_mask:0xf bank_mask:0xf bound_ctrl:1
	v_mul_f32_e32 v93, v43, v43
	v_mul_f32_e32 v94, v45, v45
	v_mul_f32_e32 v95, v39, v39
	v_mul_f32_e32 v96, v41, v41
	v_add_f32_e32 v88, v88, v90
	v_add_f32_dpp v89, v89, v89 row_half_mirror row_mask:0xf bank_mask:0xf bound_ctrl:1
	v_fmac_f32_e32 v91, v46, v46
	v_fmac_f32_e32 v92, v48, v48
	v_fmac_f32_e32 v93, v42, v42
	v_fmac_f32_e32 v94, v44, v44
	v_mul_f32_e32 v97, v35, v35
	v_mul_f32_e32 v98, v37, v37
	v_fmac_f32_e32 v95, v38, v38
	v_fmac_f32_e32 v96, v40, v40
	v_fmamk_f32 v88, v88, 0x3a800000, v86
	v_add_f32_dpp v89, v89, v89 row_mirror row_mask:0xf bank_mask:0xf bound_ctrl:1
	v_add_f32_e32 v90, v91, v92
	v_add_f32_e32 v91, v93, v94
	v_fmac_f32_e32 v97, v34, v34
	v_fmac_f32_e32 v98, v36, v36
	v_add_f32_e32 v92, v95, v96
	v_mul_f32_e32 v94, 0x4f800000, v88
	v_mov_b32_e32 v95, v89
	v_add_f32_e32 v90, v90, v91
	v_cmp_gt_f32_e32 vcc, s3, v88
	v_add_f32_e32 v93, v97, v98
	v_permlane16_swap_b32_e32 v89, v95
	v_cndmask_b32_e32 v88, v88, v94, vcc
	v_add_f32_e32 v90, v90, v92
	v_sqrt_f32_e32 v91, v88
	v_add_f32_e32 v89, v89, v95
	v_add_f32_e32 v90, v90, v93
	v_mov_b32_e32 v92, v89
	s_nop 1
	v_permlane32_swap_b32_e32 v89, v92
	v_add_f32_dpp v90, v90, v90 quad_perm:[1,0,3,2] row_mask:0xf bank_mask:0xf bound_ctrl:1
	v_mul_f32_e32 v93, v31, v31
	v_mul_f32_e32 v94, v33, v33
	v_add_f32_dpp v90, v90, v90 quad_perm:[2,3,0,1] row_mask:0xf bank_mask:0xf bound_ctrl:1
	v_mul_f32_e32 v95, v27, v27
	v_mul_f32_e32 v96, v29, v29
	v_mul_f32_e32 v97, v23, v23
	v_mul_f32_e32 v98, v25, v25
	v_mul_f32_e32 v99, v19, v19
	v_mul_f32_e32 v100, v21, v21
	v_add_f32_e32 v89, v89, v92
	v_add_f32_dpp v90, v90, v90 row_half_mirror row_mask:0xf bank_mask:0xf bound_ctrl:1
	v_fmac_f32_e32 v93, v30, v30
	v_fmac_f32_e32 v94, v32, v32
	v_fmac_f32_e32 v95, v26, v26
	v_fmac_f32_e32 v96, v28, v28
	v_fmac_f32_e32 v97, v22, v22
	v_fmac_f32_e32 v98, v24, v24
	v_fmac_f32_e32 v99, v18, v18
	v_fmac_f32_e32 v100, v20, v20
	v_add_u32_e32 v92, -1, v91
	v_fmamk_f32 v89, v89, 0x3a800000, v86
	v_add_f32_dpp v90, v90, v90 row_mirror row_mask:0xf bank_mask:0xf bound_ctrl:1
	v_add_u32_e32 v101, 1, v91
	v_add_f32_e32 v93, v93, v94
	v_add_f32_e32 v94, v95, v96
	v_add_f32_e32 v95, v97, v98
	v_add_f32_e32 v96, v99, v100
	v_fma_f32 v97, -v92, v91, v88
	v_mul_f32_e32 v99, 0x4f800000, v89
	v_cmp_gt_f32_e64 s[0:1], s3, v89
	v_mov_b32_e32 v100, v90
	v_fma_f32 v98, -v101, v91, v88
	v_add_f32_e32 v93, v93, v94
	v_cmp_ge_f32_e64 s[4:5], 0, v97
	v_cndmask_b32_e64 v89, v89, v99, s[0:1]
	v_permlane16_swap_b32_e32 v90, v100
	v_cndmask_b32_e64 v91, v91, v92, s[4:5]
	v_add_f32_e32 v92, v93, v95
	v_cmp_lt_f32_e64 s[4:5], 0, v98
	v_sqrt_f32_e32 v93, v89
	v_add_f32_e32 v90, v90, v100
	v_cndmask_b32_e64 v91, v91, v101, s[4:5]
	v_add_f32_e32 v92, v92, v96
	v_mov_b32_e32 v95, v90
	v_mul_f32_e32 v94, 0x37800000, v91
	v_add_f32_dpp v92, v92, v92 quad_perm:[1,0,3,2] row_mask:0xf bank_mask:0xf bound_ctrl:1
	v_permlane32_swap_b32_e32 v90, v95
	v_cndmask_b32_e32 v91, v91, v94, vcc
	v_add_f32_dpp v92, v92, v92 quad_perm:[2,3,0,1] row_mask:0xf bank_mask:0xf bound_ctrl:1
	v_cmp_class_f32_e32 vcc, v88, v87
	v_add_f32_e32 v90, v90, v95
	v_add_u32_e32 v95, -1, v93
	v_cndmask_b32_e32 v88, v91, v88, vcc
	v_add_f32_dpp v91, v92, v92 row_half_mirror row_mask:0xf bank_mask:0xf bound_ctrl:1
	v_fmamk_f32 v90, v90, 0x3a800000, v86
	v_div_scale_f32 v92, s[4:5], v88, v88, 1.0
	v_add_u32_e32 v96, 1, v93
	v_add_f32_dpp v91, v91, v91 row_mirror row_mask:0xf bank_mask:0xf bound_ctrl:1
; __device__ __forceinline__ float wave_sum(float v) { v = row16_sum(v); v = swap_add16(v, v); return swap_add32(v, v); }
; __device__ __forceinline__ unsigned pk2(float lo, float hi) { return f2bf(lo) | (f2bf(hi) << 16); }
; __global__ void __launch_bounds__(NWAVES * 64, 2) mk_fwd(Params P) {
;     ...
;             for (int q = 0; q < 4; ++q) { float s = 0.f;
; #pragma unroll
;                 for (int j = 0; j < 4; ++j) s += (v[q][j][0] * v[q][j][0] + v[q][j][1] * v[q][j][1]) + (v[q][j][2] * v[q][j][2] + v[q][j][3] * v[q][j][3]);
;                 const float rstd = 1.0f / sqrtf(wave_sum(s) * (1.0f / D) + EPS);
;                 unsigned long long* o8 = (unsigned long long*)(XN + (size_t)(m0 + q) * D) + lane;
; #pragma unroll
;                 for (int j = 0; j < 4; ++j) o8[64 * j] = (unsigned long long)pk2(v[q][j][0] * rstd * wn[j][0], v[q][j][1] * rstd * wn[j][1]) | ((unsigned long long)pk2(v[q][j][2] * rstd * wn[j][2], v[q][j][3] * rstd * wn[j][3]) << 32); }
	v_fma_f32 v98, -v95, v93, v89
	v_mul_f32_e32 v100, 0x4f800000, v90
	v_cmp_gt_f32_e64 s[8:9], s3, v90
	v_rcp_f32_e32 v97, v92
	v_fma_f32 v99, -v96, v93, v89
	v_mov_b32_e32 v101, v91
	v_cmp_ge_f32_e64 s[4:5], 0, v98
	v_cndmask_b32_e64 v90, v90, v100, s[8:9]
	v_permlane16_swap_b32_e32 v91, v101
	v_cndmask_b32_e64 v93, v93, v95, s[4:5]
	v_cmp_lt_f32_e64 s[4:5], 0, v99
	v_sqrt_f32_e32 v95, v90
	v_add_f32_e32 v91, v91, v101
	v_cndmask_b32_e64 v93, v93, v96, s[4:5]
	v_mul_f32_e32 v96, 0x37800000, v93
	v_mov_b32_e32 v98, v91
	v_fma_f32 v99, -v92, v97, 1.0
	v_cndmask_b32_e64 v93, v93, v96, s[0:1]
	v_cmp_class_f32_e64 s[0:1], v89, v87
	v_permlane32_swap_b32_e32 v91, v98
	v_div_scale_f32 v94, vcc, 1.0, v88, 1.0
	v_fmac_f32_e32 v97, v99, v97
	v_cndmask_b32_e64 v89, v93, v89, s[0:1]
	v_add_f32_e32 v91, v91, v98
	v_add_u32_e32 v99, -1, v95
	v_mul_f32_e32 v93, v94, v97
	v_div_scale_f32 v96, s[0:1], v89, v89, 1.0
	v_add_u32_e32 v100, 1, v95
	v_fmamk_f32 v91, v91, 0x3a800000, v86
	v_fma_f32 v103, -v99, v95, v90
	v_fma_f32 v101, -v92, v93, v94
	v_fma_f32 v104, -v100, v95, v90
	v_mul_f32_e32 v105, 0x4f800000, v91
	v_cmp_gt_f32_e64 s[6:7], s3, v91
	v_cmp_ge_f32_e64 s[0:1], 0, v103
	v_rcp_f32_e32 v102, v96
	v_fmac_f32_e32 v93, v101, v97
	v_cndmask_b32_e64 v95, v95, v99, s[0:1]
	v_cmp_lt_f32_e64 s[0:1], 0, v104
	v_cndmask_b32_e64 v91, v91, v105, s[6:7]
	v_fma_f32 v92, -v92, v93, v94
	v_cndmask_b32_e64 v94, v95, v100, s[0:1]
	v_sqrt_f32_e32 v95, v91
	v_div_fmas_f32 v92, v92, v97, v93
	v_mul_f32_e32 v93, 0x37800000, v94
	v_div_fixup_f32 v88, v92, v88, 1.0
	v_fma_f32 v92, -v96, v102, 1.0
	v_cndmask_b32_e64 v93, v94, v93, s[8:9]
	v_cmp_class_f32_e32 vcc, v90, v87
	v_div_scale_f32 v98, s[4:5], 1.0, v89, 1.0
	v_mul_f32_e32 v78, v88, v78
	v_mul_f32_e32 v79, v88, v79
	v_mul_f32_e32 v80, v88, v80
	v_mul_f32_e32 v81, v88, v81
	v_mul_f32_e32 v74, v88, v74
	v_mul_f32_e32 v75, v88, v75
	v_mul_f32_e32 v76, v88, v76
	v_mul_f32_e32 v77, v88, v77
	v_mul_f32_e32 v70, v88, v70
	v_mul_f32_e32 v71, v88, v71
	v_mul_f32_e32 v72, v88, v72
	v_mul_f32_e32 v73, v88, v73
	v_mul_f32_e32 v66, v88, v66
	v_mul_f32_e32 v67, v88, v67
	v_mul_f32_e32 v68, v88, v68
	v_mul_f32_e32 v69, v88, v69
	v_fmac_f32_e32 v102, v92, v102
	v_cndmask_b32_e32 v88, v93, v90, vcc
	v_add_u32_e32 v94, -1, v95
	v_mul_f32_e32 v78, v78, v14
	v_mul_f32_e32 v80, v80, v16
	v_mul_f32_e32 v74, v74, v10
	v_mul_f32_e32 v67, v67, v3
	v_mul_f32_e32 v68, v68, v4
	v_mul_f32_e32 v90, v98, v102
	v_div_scale_f32 v92, s[0:1], v88, v88, 1.0
	v_add_u32_e32 v97, 1, v95
	v_fma_f32 v118, -v94, v95, v91
	v_mul_f32_e32 v79, v79, v15
	v_mul_f32_e32 v81, v81, v17
	v_mul_f32_e32 v75, v75, v11
	v_mul_f32_e32 v76, v76, v12
	v_mul_f32_e32 v70, v70, v6
	v_mul_f32_e32 v72, v72, v8
	v_mul_f32_e32 v66, v66, v2
	v_mul_f32_e32 v69, v69, v5
	v_bfe_u32 v99, v78, 16, 1
	v_bfe_u32 v101, v80, 16, 1
	v_bfe_u32 v104, v74, 16, 1
	v_bfe_u32 v113, v67, 16, 1
	v_bfe_u32 v114, v68, 16, 1
	v_fma_f32 v116, -v96, v90, v98
	v_rcp_f32_e32 v117, v92
	v_fma_f32 v119, -v97, v95, v91
	v_cmp_ge_f32_e32 vcc, 0, v118
	v_mul_f32_e32 v77, v77, v13
	v_mul_f32_e32 v71, v71, v7
	v_mul_f32_e32 v73, v73, v9
	v_bfe_u32 v100, v79, 16, 1
	v_bfe_u32 v103, v81, 16, 1
	v_bfe_u32 v105, v75, 16, 1
	v_bfe_u32 v106, v76, 16, 1
	v_bfe_u32 v108, v70, 16, 1
	v_bfe_u32 v110, v72, 16, 1
	v_bfe_u32 v112, v66, 16, 1
	v_bfe_u32 v115, v69, 16, 1
	v_add3_u32 v78, v78, v99, s12
	v_add3_u32 v80, v80, v101, s12
	v_add3_u32 v74, v74, v104, s12
	v_add3_u32 v99, v67, v113, s12
	v_add3_u32 v67, v68, v114, s12
	v_fmac_f32_e32 v90, v116, v102
	v_cndmask_b32_e32 v68, v95, v94, vcc
	v_cmp_lt_f32_e32 vcc, 0, v119
	v_bfe_u32 v107, v77, 16, 1
	v_bfe_u32 v109, v71, 16, 1
	v_bfe_u32 v111, v73, 16, 1
	v_add3_u32 v79, v79, v100, s12
	v_add3_u32 v81, v81, v103, s12
	v_add3_u32 v75, v75, v105, s12
	v_add3_u32 v76, v76, v106, s12
	v_add3_u32 v70, v70, v108, s12
	v_add3_u32 v72, v72, v110, s12
	v_add3_u32 v66, v66, v112, s12
	v_add3_u32 v100, v69, v115, s12
	v_lshrrev_b32_e32 v69, 16, v78
	v_lshrrev_b32_e32 v78, 16, v80
	v_lshrrev_b32_e32 v74, 16, v74
	v_fma_f32 v95, -v96, v90, v98
	v_cndmask_b32_e32 v96, v68, v97, vcc
	s_mov_b64 vcc, s[4:5]
	v_add3_u32 v77, v77, v107, s12
	v_add3_u32 v71, v71, v109, s12
	v_add3_u32 v73, v73, v111, s12
	v_lshrrev_b32_e32 v76, 16, v76
	v_lshrrev_b32_e32 v70, 16, v70
	v_lshrrev_b32_e32 v72, 16, v72
	v_lshrrev_b32_e32 v80, 16, v66
	v_lshrrev_b32_e32 v94, 16, v67
	v_and_or_b32 v66, v79, s13, v69
	v_and_or_b32 v67, v81, s13, v78
	v_and_or_b32 v68, v75, s13, v74
	v_div_fmas_f32 v74, v95, v102, v90
	v_mul_f32_e32 v75, 0x37800000, v96
	v_and_or_b32 v69, v77, s13, v76
	v_and_or_b32 v70, v71, s13, v70
	v_and_or_b32 v71, v73, s13, v72
	v_and_or_b32 v72, v99, s13, v80
	v_and_or_b32 v73, v100, s13, v94
	global_store_dwordx2 v[82:83], v[66:67], off
	global_store_dwordx2 v[82:83], v[68:69], off offset:512
	global_store_dwordx2 v[82:83], v[70:71], off offset:1024
	global_store_dwordx2 v[82:83], v[72:73], off offset:1536
	v_div_fixup_f32 v66, v74, v89, 1.0
	v_fma_f32 v67, -v92, v117, 1.0
	v_cndmask_b32_e64 v68, v96, v75, s[6:7]
	v_cmp_class_f32_e32 vcc, v91, v87
	v_div_scale_f32 v93, s[0:1], 1.0, v88, 1.0
	v_mul_f32_e32 v62, v66, v62
	v_mul_f32_e32 v63, v66, v63
	v_mul_f32_e32 v64, v66, v64
	v_mul_f32_e32 v65, v66, v65
	v_mul_f32_e32 v58, v66, v58
	v_mul_f32_e32 v59, v66, v59
	v_mul_f32_e32 v60, v66, v60
	v_mul_f32_e32 v61, v66, v61
	v_mul_f32_e32 v54, v66, v54
	v_mul_f32_e32 v55, v66, v55
	v_mul_f32_e32 v56, v66, v56
	v_mul_f32_e32 v57, v66, v57
	v_mul_f32_e32 v50, v66, v50
	v_mul_f32_e32 v51, v66, v51
	v_mul_f32_e32 v52, v66, v52
	v_mul_f32_e32 v53, v66, v53
	v_fmac_f32_e32 v117, v67, v117
; __device__ __forceinline__ float wave_sum(float v) { v = row16_sum(v); v = swap_add16(v, v); return swap_add32(v, v); }
; __device__ __forceinline__ unsigned pk2(float lo, float hi) { return f2bf(lo) | (f2bf(hi) << 16); }
; __global__ void __launch_bounds__(NWAVES * 64, 2) mk_fwd(Params P) {
;     ...
;                 const float rstd = 1.0f / sqrtf(wave_sum(s) * (1.0f / D) + EPS);
;                 unsigned long long* o8 = (unsigned long long*)(XN + (size_t)(m0 + q) * D) + lane;
; #pragma unroll
;                 for (int j = 0; j < 4; ++j) o8[64 * j] = (unsigned long long)pk2(v[q][j][0] * rstd * wn[j][0], v[q][j][1] * rstd * wn[j][1]) | ((unsigned long long)pk2(v[q][j][2] * rstd * wn[j][2], v[q][j][3] * rstd * wn[j][3]) << 32); }
	v_cndmask_b32_e32 v66, v68, v91, vcc
	v_mul_f32_e32 v62, v62, v14
	v_mul_f32_e32 v64, v64, v16
	v_mul_f32_e32 v58, v58, v10
	v_mul_f32_e32 v67, v93, v117
	v_div_scale_f32 v68, s[4:5], v66, v66, 1.0
	v_mul_f32_e32 v63, v63, v15
	v_mul_f32_e32 v65, v65, v17
	v_mul_f32_e32 v59, v59, v11
	v_mul_f32_e32 v60, v60, v12
	v_mul_f32_e32 v54, v54, v6
	v_mul_f32_e32 v56, v56, v8
	v_mul_f32_e32 v50, v50, v2
	v_mul_f32_e32 v51, v51, v3
	v_mul_f32_e32 v52, v52, v4
	v_mul_f32_e32 v53, v53, v5
	v_bfe_u32 v70, v62, 16, 1
	v_bfe_u32 v72, v64, 16, 1
	v_bfe_u32 v74, v58, 16, 1
	v_fma_f32 v95, -v92, v67, v93
	v_rcp_f32_e32 v96, v68
	v_mul_f32_e32 v61, v61, v13
	v_mul_f32_e32 v55, v55, v7
	v_mul_f32_e32 v57, v57, v9
	v_bfe_u32 v71, v63, 16, 1
	v_bfe_u32 v73, v65, 16, 1
	v_bfe_u32 v75, v59, 16, 1
	v_bfe_u32 v76, v60, 16, 1
	v_bfe_u32 v78, v54, 16, 1
	v_bfe_u32 v80, v56, 16, 1
	v_bfe_u32 v89, v50, 16, 1
	v_bfe_u32 v90, v51, 16, 1
	v_bfe_u32 v91, v52, 16, 1
	v_bfe_u32 v94, v53, 16, 1
	v_add3_u32 v62, v62, v70, s12
	v_add3_u32 v64, v64, v72, s12
	v_add3_u32 v58, v58, v74, s12
	v_fmac_f32_e32 v67, v95, v117
	v_bfe_u32 v77, v61, 16, 1
	v_bfe_u32 v79, v55, 16, 1
	v_bfe_u32 v81, v57, 16, 1
	v_add3_u32 v63, v63, v71, s12
	v_add3_u32 v65, v65, v73, s12
	v_add3_u32 v59, v59, v75, s12
	v_add3_u32 v60, v60, v76, s12
	v_add3_u32 v54, v54, v78, s12
	v_add3_u32 v56, v56, v80, s12
	v_add3_u32 v50, v50, v89, s12
	v_add3_u32 v70, v51, v90, s12
	v_add3_u32 v51, v52, v91, s12
	v_add3_u32 v71, v53, v94, s12
	v_lshrrev_b32_e32 v52, 16, v62
	v_lshrrev_b32_e32 v53, 16, v64
	v_lshrrev_b32_e32 v58, 16, v58
	v_fma_f32 v72, -v92, v67, v93
	s_mov_b64 vcc, s[0:1]
	v_add3_u32 v61, v61, v77, s12
	v_add3_u32 v55, v55, v79, s12
	v_add3_u32 v57, v57, v81, s12
	v_lshrrev_b32_e32 v60, 16, v60
	v_lshrrev_b32_e32 v54, 16, v54
	v_lshrrev_b32_e32 v56, 16, v56
	v_lshrrev_b32_e32 v62, 16, v50
	v_lshrrev_b32_e32 v64, 16, v51
	v_and_or_b32 v50, v63, s13, v52
	v_and_or_b32 v51, v65, s13, v53
	v_and_or_b32 v52, v59, s13, v58
	v_div_fmas_f32 v58, v72, v117, v67
	v_and_or_b32 v53, v61, s13, v60
	v_and_or_b32 v54, v55, s13, v54
	v_and_or_b32 v55, v57, s13, v56
	v_and_or_b32 v56, v70, s13, v62
	v_and_or_b32 v57, v71, s13, v64
	global_store_dwordx2 v[82:83], v[50:51], off offset:2048
	global_store_dwordx2 v[82:83], v[52:53], off offset:2560
	global_store_dwordx2 v[82:83], v[54:55], off offset:3072
	global_store_dwordx2 v[82:83], v[56:57], off offset:3584
	v_div_fixup_f32 v50, v58, v88, 1.0
	v_fma_f32 v51, -v68, v96, 1.0
	v_div_scale_f32 v69, s[4:5], 1.0, v66, 1.0
	v_mul_f32_e32 v46, v50, v46
	v_mul_f32_e32 v48, v50, v48
	v_mul_f32_e32 v42, v50, v42
	v_fmac_f32_e32 v96, v51, v96
	v_mul_f32_e32 v47, v50, v47
	v_mul_f32_e32 v49, v50, v49
	v_mul_f32_e32 v43, v50, v43
	v_mul_f32_e32 v44, v50, v44
	v_mul_f32_e32 v45, v50, v45
	v_mul_f32_e32 v38, v50, v38
	v_mul_f32_e32 v39, v50, v39
	v_mul_f32_e32 v40, v50, v40
	v_mul_f32_e32 v41, v50, v41
	v_mul_f32_e32 v34, v50, v34
	v_mul_f32_e32 v35, v50, v35
	v_mul_f32_e32 v36, v50, v36
	v_mul_f32_e32 v37, v50, v37
	v_mul_f32_e32 v46, v46, v14
	v_mul_f32_e32 v48, v48, v16
	v_mul_f32_e32 v42, v42, v10
	v_mul_f32_e32 v50, v69, v96
	v_mul_f32_e32 v47, v47, v15
	v_mul_f32_e32 v49, v49, v17
	v_mul_f32_e32 v43, v43, v11
	v_mul_f32_e32 v44, v44, v12
	v_mul_f32_e32 v38, v38, v6
	v_mul_f32_e32 v40, v40, v8
	v_mul_f32_e32 v34, v34, v2
	v_mul_f32_e32 v35, v35, v3
	v_mul_f32_e32 v36, v36, v4
	v_mul_f32_e32 v37, v37, v5
	v_bfe_u32 v51, v46, 16, 1
	v_bfe_u32 v53, v48, 16, 1
	v_bfe_u32 v55, v42, 16, 1
	v_fma_f32 v70, -v68, v50, v69
	v_mul_f32_e32 v45, v45, v13
	v_mul_f32_e32 v39, v39, v7
	v_mul_f32_e32 v41, v41, v9
	v_bfe_u32 v52, v47, 16, 1
	v_bfe_u32 v54, v49, 16, 1
	v_bfe_u32 v56, v43, 16, 1
	v_bfe_u32 v57, v44, 16, 1
	v_bfe_u32 v59, v38, 16, 1
	v_bfe_u32 v61, v40, 16, 1
	v_bfe_u32 v63, v34, 16, 1
	v_bfe_u32 v64, v35, 16, 1
	v_bfe_u32 v65, v36, 16, 1
	v_bfe_u32 v67, v37, 16, 1
	v_add3_u32 v46, v46, v51, s12
	v_add3_u32 v48, v48, v53, s12
	v_add3_u32 v42, v42, v55, s12
	v_fmac_f32_e32 v50, v70, v96
; __device__ __forceinline__ float wave_sum(float v) { v = row16_sum(v); v = swap_add16(v, v); return swap_add32(v, v); }
; __device__ __forceinline__ unsigned pk2(float lo, float hi) { return f2bf(lo) | (f2bf(hi) << 16); }
; __global__ void __launch_bounds__(NWAVES * 64, 2) mk_fwd(Params P) {
;     ...
;           for (int m0 = gw * 4; m0 < M; m0 += NGW * 4) {
;             f32x4 v[4][4];
; #pragma unroll
;             for (int q = 0; q < 4; ++q) { const f32x4* xr = (const f32x4*)xrow(P.xp, P.xs, m0 + q) + lane;
; #pragma unroll
;                 for (int j = 0; j < 4; ++j) v[q][j] = xr[64 * j]; }
; #pragma unroll
;             for (int q = 0; q < 4; ++q) { float s = 0.f;
; #pragma unroll
;                 for (int j = 0; j < 4; ++j) s += (v[q][j][0] * v[q][j][0] + v[q][j][1] * v[q][j][1]) + (v[q][j][2] * v[q][j][2] + v[q][j][3] * v[q][j][3]);
;                 const float rstd = 1.0f / sqrtf(wave_sum(s) * (1.0f / D) + EPS);
;                 unsigned long long* o8 = (unsigned long long*)(XN + (size_t)(m0 + q) * D) + lane;
; #pragma unroll
;                 for (int j = 0; j < 4; ++j) o8[64 * j] = (unsigned long long)pk2(v[q][j][0] * rstd * wn[j][0], v[q][j][1] * rstd * wn[j][1]) | ((unsigned long long)pk2(v[q][j][2] * rstd * wn[j][2], v[q][j][3] * rstd * wn[j][3]) << 32); }
	v_bfe_u32 v58, v45, 16, 1
	v_bfe_u32 v60, v39, 16, 1
	v_bfe_u32 v62, v41, 16, 1
	v_add3_u32 v47, v47, v52, s12
	v_add3_u32 v49, v49, v54, s12
	v_add3_u32 v43, v43, v56, s12
	v_add3_u32 v44, v44, v57, s12
	v_add3_u32 v38, v38, v59, s12
	v_add3_u32 v40, v40, v61, s12
	v_add3_u32 v34, v34, v63, s12
	v_add3_u32 v51, v35, v64, s12
	v_add3_u32 v35, v36, v65, s12
	v_add3_u32 v52, v37, v67, s12
	v_lshrrev_b32_e32 v36, 16, v46
	v_lshrrev_b32_e32 v37, 16, v48
	v_lshrrev_b32_e32 v42, 16, v42
	v_fma_f32 v53, -v68, v50, v69
	s_mov_b64 vcc, s[4:5]
	v_add3_u32 v45, v45, v58, s12
	v_add3_u32 v39, v39, v60, s12
	v_add3_u32 v41, v41, v62, s12
	v_lshrrev_b32_e32 v44, 16, v44
	v_lshrrev_b32_e32 v38, 16, v38
	v_lshrrev_b32_e32 v40, 16, v40
	v_lshrrev_b32_e32 v46, 16, v34
	v_lshrrev_b32_e32 v48, 16, v35
	v_and_or_b32 v34, v47, s13, v36
	v_and_or_b32 v35, v49, s13, v37
	v_and_or_b32 v36, v43, s13, v42
	v_div_fmas_f32 v42, v53, v96, v50
	v_and_or_b32 v37, v45, s13, v44
	v_and_or_b32 v38, v39, s13, v38
	v_and_or_b32 v39, v41, s13, v40
	v_and_or_b32 v40, v51, s13, v46
	v_and_or_b32 v41, v52, s13, v48
	global_store_dwordx2 v[84:85], v[34:35], off
	global_store_dwordx2 v[84:85], v[36:37], off offset:512
	global_store_dwordx2 v[84:85], v[38:39], off offset:1024
	global_store_dwordx2 v[84:85], v[40:41], off offset:1536
	v_div_fixup_f32 v34, v42, v66, 1.0
	v_mul_f32_e32 v30, v34, v30
	v_mul_f32_e32 v32, v34, v32
	v_mul_f32_e32 v31, v34, v31
	v_mul_f32_e32 v33, v34, v33
	v_mul_f32_e32 v26, v34, v26
	v_mul_f32_e32 v28, v34, v28
	v_mul_f32_e32 v22, v34, v22
	v_mul_f32_e32 v24, v34, v24
	v_mul_f32_e32 v18, v34, v18
	v_mul_f32_e32 v19, v34, v19
	v_mul_f32_e32 v20, v34, v20
	v_mul_f32_e32 v21, v34, v21
	v_mul_f32_e32 v30, v30, v14
	v_mul_f32_e32 v32, v32, v16
	v_mul_f32_e32 v27, v34, v27
	v_mul_f32_e32 v29, v34, v29
	v_mul_f32_e32 v23, v34, v23
	v_mul_f32_e32 v25, v34, v25
	v_mul_f32_e32 v31, v31, v15
	v_mul_f32_e32 v33, v33, v17
	v_mul_f32_e32 v26, v26, v10
	v_mul_f32_e32 v28, v28, v12
	v_mul_f32_e32 v22, v22, v6
	v_mul_f32_e32 v24, v24, v8
	v_mul_f32_e32 v18, v18, v2
	v_mul_f32_e32 v19, v19, v3
	v_mul_f32_e32 v20, v20, v4
	v_mul_f32_e32 v21, v21, v5
	v_bfe_u32 v34, v30, 16, 1
	v_bfe_u32 v36, v32, 16, 1
	v_mul_f32_e32 v27, v27, v11
	v_mul_f32_e32 v29, v29, v13
	v_mul_f32_e32 v23, v23, v7
	v_mul_f32_e32 v25, v25, v9
	v_bfe_u32 v35, v31, 16, 1
	v_bfe_u32 v37, v33, 16, 1
	v_bfe_u32 v38, v26, 16, 1
	v_bfe_u32 v40, v28, 16, 1
	v_bfe_u32 v42, v22, 16, 1
	v_bfe_u32 v44, v24, 16, 1
	v_bfe_u32 v46, v18, 16, 1
	v_bfe_u32 v47, v19, 16, 1
	v_bfe_u32 v48, v20, 16, 1
	v_bfe_u32 v49, v21, 16, 1
	v_add3_u32 v30, v30, v34, s12
	v_add3_u32 v32, v32, v36, s12
	v_bfe_u32 v39, v27, 16, 1
	v_bfe_u32 v41, v29, 16, 1
	v_bfe_u32 v43, v23, 16, 1
	v_bfe_u32 v45, v25, 16, 1
	v_add3_u32 v31, v31, v35, s12
	v_add3_u32 v33, v33, v37, s12
	v_add3_u32 v26, v26, v38, s12
	v_add3_u32 v28, v28, v40, s12
	v_add3_u32 v22, v22, v42, s12
	v_add3_u32 v24, v24, v44, s12
	v_add3_u32 v18, v18, v46, s12
	v_add3_u32 v34, v19, v47, s12
	v_add3_u32 v19, v20, v48, s12
	v_add3_u32 v35, v21, v49, s12
	v_lshrrev_b32_e32 v20, 16, v30
	v_lshrrev_b32_e32 v21, 16, v32
	v_lshl_add_u64 v[82:83], v[82:83], 0, s[42:43]
	v_add3_u32 v27, v27, v39, s12
	v_add3_u32 v29, v29, v41, s12
	v_add3_u32 v23, v23, v43, s12
	v_add3_u32 v25, v25, v45, s12
	v_lshrrev_b32_e32 v26, 16, v26
	v_lshrrev_b32_e32 v28, 16, v28
	v_lshrrev_b32_e32 v22, 16, v22
	v_lshrrev_b32_e32 v24, 16, v24
	v_lshrrev_b32_e32 v30, 16, v18
	v_lshrrev_b32_e32 v32, 16, v19
	v_and_or_b32 v18, v31, s13, v20
	v_and_or_b32 v19, v33, s13, v21
	v_and_or_b32 v20, v27, s13, v26
	v_and_or_b32 v21, v29, s13, v28
	v_and_or_b32 v22, v23, s13, v22
	v_and_or_b32 v23, v25, s13, v24
	v_and_or_b32 v24, v34, s13, v30
	v_and_or_b32 v25, v35, s13, v32
	global_store_dwordx2 v[84:85], v[18:19], off offset:2048
	global_store_dwordx2 v[84:85], v[20:21], off offset:2560
	global_store_dwordx2 v[84:85], v[22:23], off offset:3072
	global_store_dwordx2 v[84:85], v[24:25], off offset:3584
	s_cmp_lg_u32 s98, 0
	s_cbranch_scc0 .LBB0_210

; __global__ void __launch_bounds__(NWAVES * 64, 2) mk_fwd(Params P) {
	.amdhsa_kernel _Z6mk_fwd6Params
		.amdhsa_group_segment_fixed_size 0
		.amdhsa_private_segment_fixed_size 0
		.amdhsa_kernarg_size 424
		.amdhsa_user_sgpr_count 2
		.amdhsa_user_sgpr_dispatch_ptr 0
		.amdhsa_user_sgpr_queue_ptr 0
		.amdhsa_user_sgpr_kernarg_segment_ptr 1
		.amdhsa_user_sgpr_dispatch_id 0
		.amdhsa_user_sgpr_kernarg_preload_length 0
		.amdhsa_user_sgpr_kernarg_preload_offset 0
		.amdhsa_user_sgpr_private_segment_size 0
		.amdhsa_uses_dynamic_stack 0
		.amdhsa_enable_private_segment 0
		.amdhsa_system_sgpr_workgroup_id_x 1
		.amdhsa_system_sgpr_workgroup_id_y 0
		.amdhsa_system_sgpr_workgroup_id_z 0
		.amdhsa_system_sgpr_workgroup_info 0
		.amdhsa_system_vgpr_workitem_id 2
		.amdhsa_next_free_vgpr 253
		.amdhsa_next_free_sgpr 102
		.amdhsa_accum_offset 256
		.amdhsa_reserve_vcc 1
		.amdhsa_float_round_mode_32 0
		.amdhsa_float_round_mode_16_64 0
		.amdhsa_float_denorm_mode_32 3
		.amdhsa_float_denorm_mode_16_64 3
		.amdhsa_dx10_clamp 1
		.amdhsa_ieee_mode 1
		.amdhsa_fp16_overflow 0
		.amdhsa_tg_split 0
		.amdhsa_exception_fp_ieee_invalid_op 0
		.amdhsa_exception_fp_denorm_src 0
		.amdhsa_exception_fp_ieee_div_zero 0
		.amdhsa_exception_fp_ieee_overflow 0
		.amdhsa_exception_fp_ieee_underflow 0
		.amdhsa_exception_fp_ieee_inexact 0
		.amdhsa_exception_int_div_zero 0
	.end_amdhsa_kernel

; __global__ void __launch_bounds__(NWAVES * 64, 2) mk_fwd(Params P) {
;     extern __shared__ __attribute__((aligned(16))) unsigned char lds[];
amdhsa.kernels:
  - .agpr_count:     0
    .args:
      - .offset:         0
        .size:           168
        .value_kind:     by_value
      - .offset:         168
        .size:           4
        .value_kind:     hidden_block_count_x
      - .offset:         172
        .size:           4
        .value_kind:     hidden_block_count_y
      - .offset:         176
        .size:           4
        .value_kind:     hidden_block_count_z
      - .offset:         180
        .size:           2
        .value_kind:     hidden_group_size_x
      - .offset:         182
        .size:           2
        .value_kind:     hidden_group_size_y
      - .offset:         184
        .size:           2
        .value_kind:     hidden_group_size_z
      - .offset:         186
        .size:           2
        .value_kind:     hidden_remainder_x
      - .offset:         188
        .size:           2
        .value_kind:     hidden_remainder_y
      - .offset:         190
        .size:           2
        .value_kind:     hidden_remainder_z
      - .offset:         208
        .size:           8
        .value_kind:     hidden_global_offset_x
      - .offset:         216
        .size:           8
        .value_kind:     hidden_global_offset_y
      - .offset:         224
        .size:           8
        .value_kind:     hidden_global_offset_z
      - .offset:         232
        .size:           2
        .value_kind:     hidden_grid_dims
      - .offset:         256
        .size:           8
        .value_kind:     hidden_multigrid_sync_arg
      - .offset:         288
        .size:           4
        .value_kind:     hidden_dynamic_lds_size
    .group_segment_fixed_size: 0
    .kernarg_segment_align: 8
    .kernarg_segment_size: 424
    .language:       OpenCL C
    .language_version:
      - 2
      - 0
    .max_flat_workgroup_size: 512
    .name:           _Z6mk_fwd6Params
    .private_segment_fixed_size: 0
    .sgpr_count:     108
    .sgpr_spill_count: 22
    .symbol:         _Z6mk_fwd6Params.kd
    .uniform_work_group_size: 1
    .uses_dynamic_stack: false
    .vgpr_count:     253
    .vgpr_spill_count: 0
    .wavefront_size: 64
